# weight-copy work repartitioned: P0 converts items [0,12288), P2 spare WGs [12288,25088), P5b idle WGs also convert Wgu2 tail [25088,33280)
# speedup vs baseline: 1.0270x; 1.0270x over previous
.LBB0_25:
	v_readlane_b32 s4, v241, 0
	s_cmpk_eq_i32 s4, 0x100
	s_movk_i32 s4, 0x3000
	s_cselect_b32 s14, s4, 0x8200
	s_cmp_ge_i32 s96, s14
	v_readlane_b32 s5, v241, 1
	s_cbranch_scc1 .LBB0_40
	s_lshl_b32 s4, s20, 14
	s_addk_i32 s4, 0x100
	v_lshrrev_b32_e32 v1, 5, v147
	v_and_b32_e32 v2, 31, v146
	v_lshlrev_b32_e32 v4, 3, v146
	v_lshl_add_u32 v7, v2, 2, s4
	v_mul_u32_u24_e32 v13, 0x84, v1
	v_lshrrev_b32_e32 v8, 3, v147
	v_and_b32_e32 v6, 56, v4
	v_mov_b32_e32 v3, 0
	v_mul_u32_u24_e32 v4, 0x84, v6
	v_lshlrev_b32_e32 v5, 2, v8
	v_add_u32_e32 v13, v7, v13
	v_add3_u32 v9, s4, v4, v5
	v_or_b32_e32 v10, 8, v8
	v_or_b32_e32 v11, 16, v8
	v_or_b32_e32 v12, 24, v8
	s_lshl_b32 s15, s96, 5
	s_lshl_b32 s16, s86, 5
	s_lshl_b32 s17, s96, 4
	s_lshl_b32 s18, s86, 4
	v_lshlrev_b32_e32 v4, 2, v2
	v_mov_b32_e32 v5, v3
	v_lshlrev_b32_e32 v6, 1, v6
	v_mov_b32_e32 v7, v3
	v_add_u32_e32 v14, 0x400, v13
	v_add_u32_e32 v15, 0x800, v13
	v_add_u32_e32 v16, 0xc00, v13
	v_add_u32_e32 v17, 0x1000, v13
	v_add_u32_e32 v18, 0x1400, v13
	v_add_u32_e32 v19, 0x1800, v13
	v_add_u32_e32 v20, 0x1c00, v13
	s_mov_b32 s19, s96
	s_branch .LBB0_28

.LBB0_160:
	s_cmp_lt_i32 s90, 3
	s_cselect_b64 s[2:3], -1, 0
	s_add_u32 s44, s94, 0xa400000
	s_addc_u32 s45, s95, 0
	s_add_u32 s4, s94, 0xc400000
	s_addc_u32 s5, s95, 0
	v_writelane_b32 v241, s4, 56
	s_and_b64 s[2:3], s[2:3], s[0:1]
	s_andn2_b64 vcc, exec, s[2:3]
	v_writelane_b32 v241, s5, 57
	v_writelane_b32 v241, s44, 58
	v_writelane_b32 v241, s45, 59
	s_cbranch_vccnz .LBB0_196
	v_readlane_b32 s0, v241, 0
	s_cmpk_lg_i32 s0, 0x100
	v_readlane_b32 s1, v241, 1
	s_cselect_b32 s33, s0, 0xf0
	s_cmp_ge_i32 s72, s33
	s_mov_b64 s[0:1], -1
	s_cbranch_scc0 .LBB0_178
	s_sub_i32 s0, s72, s33
	s_lshl_b32 s0, s0, 3
	s_add_i32 s0, s0, s20
	s_cmpk_gt_u32 s0, 0x31ff
	s_cbranch_scc1 .LBB0_177
	s_add_i32 s13, s0, 0x3000
	s_lshl_b32 s0, s20, 14
	s_addk_i32 s0, 0x100
	v_lshrrev_b32_e32 v1, 5, v147
	v_and_b32_e32 v2, 31, v146
	v_lshlrev_b32_e32 v4, 3, v146
	v_readlane_b32 s4, v241, 0
	v_lshl_add_u32 v7, v2, 2, s0
	v_mul_u32_u24_e32 v13, 0x84, v1
	v_lshrrev_b32_e32 v8, 3, v147
	v_and_b32_e32 v6, 56, v4
	s_sub_i32 s1, s4, s33
	v_mov_b32_e32 v3, 0
	v_mul_u32_u24_e32 v4, 0x84, v6
	v_lshlrev_b32_e32 v5, 2, v8
	v_add_u32_e32 v13, v7, v13
	s_lshl_b32 s12, s1, 3
	v_add3_u32 v9, s0, v4, v5
	v_or_b32_e32 v10, 8, v8
	v_or_b32_e32 v11, 16, v8
	v_or_b32_e32 v12, 24, v8
	s_lshl_b32 s14, s13, 5
	s_lshl_b32 s15, s1, 8
	s_lshl_b32 s16, s13, 4
	s_lshl_b32 s17, s1, 7
	v_lshlrev_b32_e32 v4, 2, v2
	v_mov_b32_e32 v5, v3
	v_lshlrev_b32_e32 v6, 1, v6
	v_mov_b32_e32 v7, v3
	v_add_u32_e32 v14, 0x400, v13
	v_add_u32_e32 v15, 0x800, v13
	v_add_u32_e32 v16, 0xc00, v13
	v_add_u32_e32 v17, 0x1000, v13
	v_add_u32_e32 v18, 0x1400, v13
	v_add_u32_e32 v19, 0x1800, v13
	v_add_u32_e32 v20, 0x1c00, v13
	v_readlane_b32 s5, v241, 1
	s_branch .LBB0_165
.LBB0_164:
	v_mul_u32_u24_e32 v2, s8, v1
	v_lshlrev_b32_e32 v2, 2, v2
	v_lshl_add_u64 v[22:23], s[6:7], 0, v[2:3]
	v_lshl_add_u64 v[22:23], v[22:23], 0, v[4:5]
	s_lshl_b64 s[6:7], s[8:9], 3
	v_lshl_add_u64 v[24:25], v[22:23], 0, s[6:7]
	v_lshl_add_u64 v[26:27], v[24:25], 0, s[6:7]
	v_lshl_add_u64 v[28:29], v[26:27], 0, s[6:7]
	v_lshl_add_u64 v[30:31], v[28:29], 0, s[6:7]
	v_lshl_add_u64 v[32:33], v[30:31], 0, s[6:7]
	v_lshl_add_u64 v[34:35], v[32:33], 0, s[6:7]
	v_lshl_add_u64 v[36:37], v[34:35], 0, s[6:7]
	global_load_dword v2, v[22:23], off nt
	global_load_dword v21, v[24:25], off nt
	s_nop 0
	global_load_dword v24, v[26:27], off nt
	global_load_dword v25, v[28:29], off nt
	s_nop 0
	global_load_dword v26, v[30:31], off nt
	global_load_dword v27, v[32:33], off nt
	global_load_dword v28, v[34:35], off nt
	global_load_dword v29, v[36:37], off nt
	v_lshl_add_u64 v[22:23], v[36:37], 0, s[6:7]
	global_load_dword v30, v[22:23], off nt
	v_lshl_add_u64 v[22:23], v[22:23], 0, s[6:7]
	global_load_dword v31, v[22:23], off nt
	v_lshl_add_u64 v[22:23], v[22:23], 0, s[6:7]
	global_load_dword v32, v[22:23], off nt
	v_lshl_add_u64 v[22:23], v[22:23], 0, s[6:7]
	global_load_dword v33, v[22:23], off nt
	v_lshl_add_u64 v[22:23], v[22:23], 0, s[6:7]
	global_load_dword v34, v[22:23], off nt
	v_lshl_add_u64 v[22:23], v[22:23], 0, s[6:7]
	global_load_dword v35, v[22:23], off nt
	v_lshl_add_u64 v[22:23], v[22:23], 0, s[6:7]
	global_load_dword v36, v[22:23], off nt
	v_lshl_add_u64 v[22:23], v[22:23], 0, s[6:7]
	global_load_dword v37, v[22:23], off nt
	v_lshl_add_u64 v[22:23], v[22:23], 0, s[6:7]
	global_load_dword v38, v[22:23], off nt
	v_lshl_add_u64 v[22:23], v[22:23], 0, s[6:7]
	global_load_dword v39, v[22:23], off nt
	v_lshl_add_u64 v[22:23], v[22:23], 0, s[6:7]
	global_load_dword v40, v[22:23], off nt
	v_lshl_add_u64 v[22:23], v[22:23], 0, s[6:7]
	global_load_dword v41, v[22:23], off nt
	v_lshl_add_u64 v[22:23], v[22:23], 0, s[6:7]
	global_load_dword v42, v[22:23], off nt
	v_lshl_add_u64 v[22:23], v[22:23], 0, s[6:7]
	global_load_dword v43, v[22:23], off nt
	v_lshl_add_u64 v[22:23], v[22:23], 0, s[6:7]
	global_load_dword v44, v[22:23], off nt
	v_lshl_add_u64 v[22:23], v[22:23], 0, s[6:7]
	global_load_dword v45, v[22:23], off nt
	v_lshl_add_u64 v[22:23], v[22:23], 0, s[6:7]
	global_load_dword v46, v[22:23], off nt
	v_lshl_add_u64 v[22:23], v[22:23], 0, s[6:7]
	global_load_dword v47, v[22:23], off nt
	v_lshl_add_u64 v[22:23], v[22:23], 0, s[6:7]
	global_load_dword v48, v[22:23], off nt
	v_lshl_add_u64 v[22:23], v[22:23], 0, s[6:7]
	global_load_dword v49, v[22:23], off nt
	v_lshl_add_u64 v[22:23], v[22:23], 0, s[6:7]
	global_load_dword v50, v[22:23], off nt
	v_lshl_add_u64 v[22:23], v[22:23], 0, s[6:7]
	global_load_dword v51, v[22:23], off nt
	v_lshl_add_u64 v[22:23], v[22:23], 0, s[6:7]
	global_load_dword v52, v[22:23], off nt
	v_lshl_add_u64 v[22:23], v[22:23], 0, s[6:7]
	global_load_dword v22, v[22:23], off nt
	s_add_i32 s13, s13, s12
	s_add_i32 s14, s14, s15
	s_add_i32 s16, s16, s17
	s_cmp_lt_i32 s13, 0x6200
	s_waitcnt vmcnt(30)
	ds_write2_b32 v13, v2, v21 offset1:66
	s_waitcnt vmcnt(28)
	ds_write2_b32 v13, v24, v25 offset0:132 offset1:198
	s_waitcnt vmcnt(26)
	ds_write2_b32 v14, v26, v27 offset0:8 offset1:74
	s_waitcnt vmcnt(24)
	ds_write2_b32 v14, v28, v29 offset0:140 offset1:206
	s_waitcnt vmcnt(22)
	ds_write2_b32 v15, v30, v31 offset0:16 offset1:82
	s_waitcnt vmcnt(20)
	ds_write2_b32 v15, v32, v33 offset0:148 offset1:214
	s_waitcnt vmcnt(18)
	ds_write2_b32 v16, v34, v35 offset0:24 offset1:90
	s_waitcnt vmcnt(16)
	ds_write2_b32 v16, v36, v37 offset0:156 offset1:222
	s_waitcnt vmcnt(14)
	ds_write2_b32 v17, v38, v39 offset0:32 offset1:98
	s_waitcnt vmcnt(12)
	ds_write2_b32 v17, v40, v41 offset0:164 offset1:230
	s_waitcnt vmcnt(10)
	ds_write2_b32 v18, v42, v43 offset0:40 offset1:106
	s_waitcnt vmcnt(8)
	ds_write2_b32 v18, v44, v45 offset0:172 offset1:238
	s_waitcnt vmcnt(6)
	ds_write2_b32 v19, v46, v47 offset0:48 offset1:114
	s_waitcnt vmcnt(4)
	ds_write2_b32 v19, v48, v49 offset0:180 offset1:246
	s_waitcnt vmcnt(2)
	ds_write2_b32 v20, v50, v51 offset0:56 offset1:122
	s_waitcnt vmcnt(0)
	ds_write2_b32 v20, v52, v22 offset0:188 offset1:254
	s_waitcnt lgkmcnt(0)
	ds_read2_b32 v[22:23], v9 offset1:33
	s_waitcnt lgkmcnt(0)
	v_cvt_pk_bf16_f32 v22, v22, v23
	ds_read2_b32 v[24:25], v9 offset0:66 offset1:99
	v_mul_u32_u24_e32 v2, s0, v8
	s_waitcnt lgkmcnt(0)
	v_cvt_pk_bf16_f32 v23, v24, v25
	ds_read2_b32 v[24:25], v9 offset0:132 offset1:165
	v_lshl_add_u64 v[28:29], s[4:5], 0, v[6:7]
	v_lshlrev_b32_e32 v2, 1, v2
	s_waitcnt lgkmcnt(0)
	v_cvt_pk_bf16_f32 v24, v24, v25
	ds_read2_b32 v[26:27], v9 offset0:198 offset1:231
	s_waitcnt lgkmcnt(0)
	v_cvt_pk_bf16_f32 v25, v26, v27
	v_lshl_add_u64 v[30:31], v[28:29], 0, v[2:3]
	ds_read2_b32 v[26:27], v9 offset0:8 offset1:41
	global_store_dwordx4 v[30:31], v[22:25], off
	v_mul_u32_u24_e32 v2, s0, v10
	v_lshlrev_b32_e32 v2, 1, v2
	s_waitcnt lgkmcnt(0)
	v_cvt_pk_bf16_f32 v22, v26, v27
	ds_read2_b32 v[24:25], v9 offset0:74 offset1:107
	s_waitcnt lgkmcnt(0)
	v_cvt_pk_bf16_f32 v23, v24, v25
	ds_read2_b32 v[24:25], v9 offset0:140 offset1:173
	s_waitcnt lgkmcnt(0)
	v_cvt_pk_bf16_f32 v24, v24, v25
	ds_read2_b32 v[26:27], v9 offset0:206 offset1:239
	s_waitcnt lgkmcnt(0)
	v_cvt_pk_bf16_f32 v25, v26, v27
	v_lshl_add_u64 v[30:31], v[28:29], 0, v[2:3]
	ds_read2_b32 v[26:27], v9 offset0:16 offset1:49
	global_store_dwordx4 v[30:31], v[22:25], off
	v_mul_u32_u24_e32 v2, s0, v11
	v_lshlrev_b32_e32 v2, 1, v2
	s_waitcnt lgkmcnt(0)
	v_cvt_pk_bf16_f32 v22, v26, v27
	ds_read2_b32 v[24:25], v9 offset0:82 offset1:115
	s_waitcnt lgkmcnt(0)
	v_cvt_pk_bf16_f32 v23, v24, v25
	ds_read2_b32 v[24:25], v9 offset0:148 offset1:181
	s_waitcnt lgkmcnt(0)
	v_cvt_pk_bf16_f32 v24, v24, v25
	ds_read2_b32 v[26:27], v9 offset0:214 offset1:247
	s_waitcnt lgkmcnt(0)
	v_cvt_pk_bf16_f32 v25, v26, v27
	v_lshl_add_u64 v[30:31], v[28:29], 0, v[2:3]
	v_mul_u32_u24_e32 v2, s0, v12
	ds_read2_b32 v[26:27], v9 offset0:24 offset1:57
	global_store_dwordx4 v[30:31], v[22:25], off
	v_lshlrev_b32_e32 v2, 1, v2
	v_lshl_add_u64 v[28:29], v[28:29], 0, v[2:3]
	s_waitcnt lgkmcnt(0)
	v_cvt_pk_bf16_f32 v22, v26, v27
	ds_read2_b32 v[24:25], v9 offset0:90 offset1:123
	s_waitcnt lgkmcnt(0)
	v_cvt_pk_bf16_f32 v23, v24, v25
	ds_read2_b32 v[24:25], v9 offset0:156 offset1:189
	s_waitcnt lgkmcnt(0)
	v_cvt_pk_bf16_f32 v24, v24, v25
	ds_read2_b32 v[26:27], v9 offset0:222 offset1:255
	s_waitcnt lgkmcnt(0)
	v_cvt_pk_bf16_f32 v25, v26, v27
	global_store_dwordx4 v[28:29], v[22:25], off
	s_waitcnt lgkmcnt(0)
	s_cbranch_scc0 .LBB0_177

.LBB0_492:
	v_readlane_b32 s0, v241, 0
	s_cmpk_lg_i32 s0, 0x100
	s_cbranch_scc1 .Lp5x_done
	s_sub_i32 s0, s72, 0x80
	s_lshl_b32 s0, s0, 3
	s_add_i32 s0, s0, s20
	s_cmpk_gt_u32 s0, 0x1fff
	s_cbranch_scc1 .Lp5x_done
	s_add_i32 s13, s0, 0x6200
	s_movk_i32 s12, 0x400
	s_lshl_b32 s0, s20, 14
	s_addk_i32 s0, 0x100
	v_lshrrev_b32_e32 v1, 5, v147
	v_and_b32_e32 v2, 31, v146
	v_lshlrev_b32_e32 v4, 3, v146
	v_lshl_add_u32 v7, v2, 2, s0
	v_mul_u32_u24_e32 v13, 0x84, v1
	v_lshrrev_b32_e32 v8, 3, v147
	v_and_b32_e32 v6, 56, v4
	v_mov_b32_e32 v3, 0
	v_mul_u32_u24_e32 v4, 0x84, v6
	v_lshlrev_b32_e32 v5, 2, v8
	v_add_u32_e32 v13, v7, v13
	v_add3_u32 v9, s0, v4, v5
	v_or_b32_e32 v10, 8, v8
	v_or_b32_e32 v11, 16, v8
	v_or_b32_e32 v12, 24, v8
	v_lshlrev_b32_e32 v4, 2, v2
	v_mov_b32_e32 v5, v3
	v_lshlrev_b32_e32 v6, 1, v6
	v_mov_b32_e32 v7, v3
	v_add_u32_e32 v14, 0x400, v13
	v_add_u32_e32 v15, 0x800, v13
	v_add_u32_e32 v16, 0xc00, v13
	v_add_u32_e32 v17, 0x1000, v13
	v_add_u32_e32 v18, 0x1400, v13
	v_add_u32_e32 v19, 0x1800, v13
	v_add_u32_e32 v20, 0x1c00, v13
.Lp5x_decode:
	s_add_i32 s0, s13, 0xaa00
	s_and_b32 s1, s0, 0xffff
	s_mul_i32 s1, s1, 0xba2f
	s_lshr_b32 s1, s1, 24
	s_mul_i32 s4, s1, 0x160
	s_sub_i32 s0, s0, s4
	s_and_b32 s4, s0, 0xffff
	s_lshl_b32 s5, s4, 5
	s_and_b32 s5, s5, 0x60
	s_bitcmp0_b32 s0, 2
	v_readlane_b32 s58, v241, 47
	v_readlane_b32 s59, v241, 48
	v_readlane_b32 s60, v241, 49
	v_readlane_b32 s61, v241, 50
	s_cselect_b32 s6, s59, s61
	s_cselect_b32 s7, s58, s60
	s_lshl_b32 s4, s4, 4
	s_and_b32 s4, s4, 0x1f80
	s_or_b32 s4, s4, s5
	s_mul_i32 s5, s1, 0x160000
	s_add_u32 s5, s7, s5
	s_addc_u32 s7, s6, 0
	s_lshl_b32 s4, s4, 2
	s_add_u32 s6, s5, s4
	s_addc_u32 s7, s7, 0
	s_lshl_b32 s0, s0, 17
	v_readlane_b32 s4, v241, 53
	s_add_u32 s0, s4, s0
	v_readlane_b32 s4, v241, 54
	s_addc_u32 s5, s4, 0
	s_lshl_b32 s1, s1, 7
	s_add_u32 s4, s0, s1
	s_addc_u32 s5, s5, 0
	s_mov_b64 s[8:9], 0x1600
	s_mov_b64 s[0:1], 0x800
	v_mul_u32_u24_e32 v2, s8, v1
	v_lshlrev_b32_e32 v2, 2, v2
	v_lshl_add_u64 v[22:23], s[6:7], 0, v[2:3]
	v_lshl_add_u64 v[22:23], v[22:23], 0, v[4:5]
	s_lshl_b64 s[6:7], s[8:9], 3
	v_lshl_add_u64 v[24:25], v[22:23], 0, s[6:7]
	v_lshl_add_u64 v[26:27], v[24:25], 0, s[6:7]
	v_lshl_add_u64 v[28:29], v[26:27], 0, s[6:7]
	v_lshl_add_u64 v[30:31], v[28:29], 0, s[6:7]
	v_lshl_add_u64 v[32:33], v[30:31], 0, s[6:7]
	v_lshl_add_u64 v[34:35], v[32:33], 0, s[6:7]
	v_lshl_add_u64 v[36:37], v[34:35], 0, s[6:7]
	global_load_dword v2, v[22:23], off nt
	global_load_dword v21, v[24:25], off nt
	s_nop 0
	global_load_dword v24, v[26:27], off nt
	global_load_dword v25, v[28:29], off nt
	s_nop 0
	global_load_dword v26, v[30:31], off nt
	global_load_dword v27, v[32:33], off nt
	global_load_dword v28, v[34:35], off nt
	global_load_dword v29, v[36:37], off nt
	v_lshl_add_u64 v[22:23], v[36:37], 0, s[6:7]
	global_load_dword v30, v[22:23], off nt
	v_lshl_add_u64 v[22:23], v[22:23], 0, s[6:7]
	global_load_dword v31, v[22:23], off nt
	v_lshl_add_u64 v[22:23], v[22:23], 0, s[6:7]
	global_load_dword v32, v[22:23], off nt
	v_lshl_add_u64 v[22:23], v[22:23], 0, s[6:7]
	global_load_dword v33, v[22:23], off nt
	v_lshl_add_u64 v[22:23], v[22:23], 0, s[6:7]
	global_load_dword v34, v[22:23], off nt
	v_lshl_add_u64 v[22:23], v[22:23], 0, s[6:7]
	global_load_dword v35, v[22:23], off nt
	v_lshl_add_u64 v[22:23], v[22:23], 0, s[6:7]
	global_load_dword v36, v[22:23], off nt
	v_lshl_add_u64 v[22:23], v[22:23], 0, s[6:7]
	global_load_dword v37, v[22:23], off nt
	v_lshl_add_u64 v[22:23], v[22:23], 0, s[6:7]
	global_load_dword v38, v[22:23], off nt
	v_lshl_add_u64 v[22:23], v[22:23], 0, s[6:7]
	global_load_dword v39, v[22:23], off nt
	v_lshl_add_u64 v[22:23], v[22:23], 0, s[6:7]
	global_load_dword v40, v[22:23], off nt
	v_lshl_add_u64 v[22:23], v[22:23], 0, s[6:7]
	global_load_dword v41, v[22:23], off nt
	v_lshl_add_u64 v[22:23], v[22:23], 0, s[6:7]
	global_load_dword v42, v[22:23], off nt
	v_lshl_add_u64 v[22:23], v[22:23], 0, s[6:7]
	global_load_dword v43, v[22:23], off nt
	v_lshl_add_u64 v[22:23], v[22:23], 0, s[6:7]
	global_load_dword v44, v[22:23], off nt
	v_lshl_add_u64 v[22:23], v[22:23], 0, s[6:7]
	global_load_dword v45, v[22:23], off nt
	v_lshl_add_u64 v[22:23], v[22:23], 0, s[6:7]
	global_load_dword v46, v[22:23], off nt
	v_lshl_add_u64 v[22:23], v[22:23], 0, s[6:7]
	global_load_dword v47, v[22:23], off nt
	v_lshl_add_u64 v[22:23], v[22:23], 0, s[6:7]
	global_load_dword v48, v[22:23], off nt
	v_lshl_add_u64 v[22:23], v[22:23], 0, s[6:7]
	global_load_dword v49, v[22:23], off nt
	v_lshl_add_u64 v[22:23], v[22:23], 0, s[6:7]
	global_load_dword v50, v[22:23], off nt
	v_lshl_add_u64 v[22:23], v[22:23], 0, s[6:7]
	global_load_dword v51, v[22:23], off nt
	v_lshl_add_u64 v[22:23], v[22:23], 0, s[6:7]
	global_load_dword v52, v[22:23], off nt
	v_lshl_add_u64 v[22:23], v[22:23], 0, s[6:7]
	global_load_dword v22, v[22:23], off nt
	s_add_i32 s13, s13, s12
	s_cmp_lt_i32 s13, 0x8200
	s_waitcnt vmcnt(30)
	ds_write2_b32 v13, v2, v21 offset1:66
	s_waitcnt vmcnt(28)
	ds_write2_b32 v13, v24, v25 offset0:132 offset1:198
	s_waitcnt vmcnt(26)
	ds_write2_b32 v14, v26, v27 offset0:8 offset1:74
	s_waitcnt vmcnt(24)
	ds_write2_b32 v14, v28, v29 offset0:140 offset1:206
	s_waitcnt vmcnt(22)
	ds_write2_b32 v15, v30, v31 offset0:16 offset1:82
	s_waitcnt vmcnt(20)
	ds_write2_b32 v15, v32, v33 offset0:148 offset1:214
	s_waitcnt vmcnt(18)
	ds_write2_b32 v16, v34, v35 offset0:24 offset1:90
	s_waitcnt vmcnt(16)
	ds_write2_b32 v16, v36, v37 offset0:156 offset1:222
	s_waitcnt vmcnt(14)
	ds_write2_b32 v17, v38, v39 offset0:32 offset1:98
	s_waitcnt vmcnt(12)
	ds_write2_b32 v17, v40, v41 offset0:164 offset1:230
	s_waitcnt vmcnt(10)
	ds_write2_b32 v18, v42, v43 offset0:40 offset1:106
	s_waitcnt vmcnt(8)
	ds_write2_b32 v18, v44, v45 offset0:172 offset1:238
	s_waitcnt vmcnt(6)
	ds_write2_b32 v19, v46, v47 offset0:48 offset1:114
	s_waitcnt vmcnt(4)
	ds_write2_b32 v19, v48, v49 offset0:180 offset1:246
	s_waitcnt vmcnt(2)
	ds_write2_b32 v20, v50, v51 offset0:56 offset1:122
	s_waitcnt vmcnt(0)
	ds_write2_b32 v20, v52, v22 offset0:188 offset1:254
	s_waitcnt lgkmcnt(0)
	ds_read2_b32 v[22:23], v9 offset1:33
	s_waitcnt lgkmcnt(0)
	v_cvt_pk_bf16_f32 v22, v22, v23
	ds_read2_b32 v[24:25], v9 offset0:66 offset1:99
	v_mul_u32_u24_e32 v2, s0, v8
	s_waitcnt lgkmcnt(0)
	v_cvt_pk_bf16_f32 v23, v24, v25
	ds_read2_b32 v[24:25], v9 offset0:132 offset1:165
	v_lshl_add_u64 v[28:29], s[4:5], 0, v[6:7]
	v_lshlrev_b32_e32 v2, 1, v2
	s_waitcnt lgkmcnt(0)
	v_cvt_pk_bf16_f32 v24, v24, v25
	ds_read2_b32 v[26:27], v9 offset0:198 offset1:231
	s_waitcnt lgkmcnt(0)
	v_cvt_pk_bf16_f32 v25, v26, v27
	v_lshl_add_u64 v[30:31], v[28:29], 0, v[2:3]
	ds_read2_b32 v[26:27], v9 offset0:8 offset1:41
	global_store_dwordx4 v[30:31], v[22:25], off
	v_mul_u32_u24_e32 v2, s0, v10
	v_lshlrev_b32_e32 v2, 1, v2
	s_waitcnt lgkmcnt(0)
	v_cvt_pk_bf16_f32 v22, v26, v27
	ds_read2_b32 v[24:25], v9 offset0:74 offset1:107
	s_waitcnt lgkmcnt(0)
	v_cvt_pk_bf16_f32 v23, v24, v25
	ds_read2_b32 v[24:25], v9 offset0:140 offset1:173
	s_waitcnt lgkmcnt(0)
	v_cvt_pk_bf16_f32 v24, v24, v25
	ds_read2_b32 v[26:27], v9 offset0:206 offset1:239
	s_waitcnt lgkmcnt(0)
	v_cvt_pk_bf16_f32 v25, v26, v27
	v_lshl_add_u64 v[30:31], v[28:29], 0, v[2:3]
	ds_read2_b32 v[26:27], v9 offset0:16 offset1:49
	global_store_dwordx4 v[30:31], v[22:25], off
	v_mul_u32_u24_e32 v2, s0, v11
	v_lshlrev_b32_e32 v2, 1, v2
	s_waitcnt lgkmcnt(0)
	v_cvt_pk_bf16_f32 v22, v26, v27
	ds_read2_b32 v[24:25], v9 offset0:82 offset1:115
	s_waitcnt lgkmcnt(0)
	v_cvt_pk_bf16_f32 v23, v24, v25
	ds_read2_b32 v[24:25], v9 offset0:148 offset1:181
	s_waitcnt lgkmcnt(0)
	v_cvt_pk_bf16_f32 v24, v24, v25
	ds_read2_b32 v[26:27], v9 offset0:214 offset1:247
	s_waitcnt lgkmcnt(0)
	v_cvt_pk_bf16_f32 v25, v26, v27
	v_lshl_add_u64 v[30:31], v[28:29], 0, v[2:3]
	v_mul_u32_u24_e32 v2, s0, v12
	ds_read2_b32 v[26:27], v9 offset0:24 offset1:57
	global_store_dwordx4 v[30:31], v[22:25], off
	v_lshlrev_b32_e32 v2, 1, v2
	v_lshl_add_u64 v[28:29], v[28:29], 0, v[2:3]
	s_waitcnt lgkmcnt(0)
	v_cvt_pk_bf16_f32 v22, v26, v27
	ds_read2_b32 v[24:25], v9 offset0:90 offset1:123
	s_waitcnt lgkmcnt(0)
	v_cvt_pk_bf16_f32 v23, v24, v25
	ds_read2_b32 v[24:25], v9 offset0:156 offset1:189
	s_waitcnt lgkmcnt(0)
	v_cvt_pk_bf16_f32 v24, v24, v25
	ds_read2_b32 v[26:27], v9 offset0:222 offset1:255
	s_waitcnt lgkmcnt(0)
	v_cvt_pk_bf16_f32 v25, v26, v27
	global_store_dwordx4 v[28:29], v[22:25], off
	s_waitcnt lgkmcnt(0)
	s_cbranch_scc1 .Lp5x_decode
